# L0 out-projection residual epilogue de-serialised: per group of 4 residual loads (shared base) loads 2..4 hoisted next to load 1 into dead GEMM fragment registers, one vmcnt(0) per group instead of pe
# speedup vs baseline: 1.0008x; 1.0008x over previous
; #define PG8_STAGE(bufoff, gbase, voff) do { _Pragma("unroll") for (int _i = 0; _i < 2; ++_i) \
;     __builtin_amdgcn_global_load_lds((const unsigned*)((const char*)(gbase) + (voff)[_i]), (LAS unsigned*)(lds + (bufoff) + ldsw + _i * 8192), 16, 0, 0); } while (0)
; #define PG8_LDA(dst, b, h) do { _Pragma("unroll") for (int m = 0; m < 4; ++m) _Pragma("unroll") for (int k = 0; k < 2; ++k) dst[m][k] = *(const LAS bf16x8*)(lds + PG8_SA(b, h) + aoff + m * 2048 + k * 1024); } while (0)
; #define PG8_LDB(dst, b, h) do { _Pragma("unroll") for (int n = 0; n < 2; ++n) _Pragma("unroll") for (int k = 0; k < 2; ++k) dst[n][k] = *(const LAS bf16x8*)(lds + PG8_SB(b, h) + boff + n * 2048 + k * 1024); } while (0)
; #define PG8_MMA(ai, bj, At, Bt) do { __builtin_amdgcn_s_setprio(1); _Pragma("unroll") for (int m = 0; m < 4; ++m) _Pragma("unroll") for (int n = 0; n < 2; ++n) _Pragma("unroll") for (int k = 0; k < 2; ++k) \
;     acc[ai][bj][m][n] = __builtin_amdgcn_mfma_f32_16x16x32_bf16(Bt[n][k], At[m][k], acc[ai][bj][m][n], 0, 0, 0); __builtin_amdgcn_s_setprio(0); } while (0)
; #define PG8_WAIT_L(n) asm volatile("s_waitcnt lgkmcnt(" #n ")" ::: "memory")
; #define PG8_BAR __builtin_amdgcn_s_barrier()
; #define PG8_SCHED __builtin_amdgcn_sched_barrier(0)
; template <class Epi, class Sched>
; __device__ __forceinline__ void gemm_phase(LAS unsigned char* lds, const Gemm g, const Sched& S, const Epi& E) {
;     ...
;       PG8_LDB(B0, 0, 0); PG8_SCHED; PG8_LDA(At, 0, 0); PG8_STAGE(PG8_SA(1, 1), a1 + hstepA, voffA);
;       PG8_WAIT_L(8); PG8_BAR; PG8_WAIT_L(0); PG8_MMA(0, 0, At, B0); PG8_BAR; PG8_SCHED;
;       PG8_LDB(B1, 0, 1); PG8_STAGE(PG8_SB(0, 0), b2, voffB);
;       PG8_BAR; PG8_WAIT_L(0); PG8_MMA(0, 1, At, B1); PG8_BAR;
;       PG8_LDA(At, 0, 1); PG8_STAGE(PG8_SA(0, 0), a2, voffA);
;       PG8_BAR; PG8_WAIT_L(0); PG8_MMA(1, 0, At, B0); PG8_BAR; PG8_SCHED;
.LBB0_448:
	s_add_u32 s7, s40, 0xffe00080
	s_addc_u32 s8, s41, -1
	s_add_i32 s9, 0, 0x10000
	v_add_u32_e32 v142, s9, v145
	ds_read_b128 v[138:141], v142
	ds_read_b128 v[148:151], v142 offset:1024
	ds_read_b128 v[152:155], v142 offset:2048
	ds_read_b128 v[156:159], v142 offset:3072
	s_cmp_eq_u32 s6, 44
	s_cselect_b32 s85, s25, s8
	s_cselect_b32 s84, vcc_lo, s7
	s_cselect_b32 s65, s35, s5
	s_cselect_b32 s64, s34, s4
	v_lshl_add_u64 v[142:143], s[40:41], 0, v[134:135]
	s_add_i32 m0, s14, 0xc000
	ds_read_b128 v[172:175], v147
	ds_read_b128 v[176:179], v147 offset:1024
	ds_read_b128 v[180:183], v147 offset:2048
	ds_read_b128 v[184:187], v147 offset:3072
	ds_read_b128 v[188:191], v147 offset:4096
	ds_read_b128 v[192:195], v147 offset:5120
	ds_read_b128 v[196:199], v147 offset:6144
	ds_read_b128 v[200:203], v147 offset:7168
	global_load_lds_dwordx4 v[142:143], off
	v_lshl_add_u64 v[142:143], s[40:41], 0, v[136:137]
	s_add_i32 m0, s14, 0xe000
	s_nop 0
	global_load_lds_dwordx4 v[142:143], off
	s_waitcnt lgkmcnt(8)
	s_barrier
	s_waitcnt lgkmcnt(0)
	s_setprio 1
	s_waitcnt lgkmcnt(0)
	v_mfma_f32_16x16x32_bf16 v[124:127], v[138:141], v[172:175], v[124:127]
	v_mfma_f32_16x16x32_bf16 v[120:123], v[152:155], v[172:175], v[120:123]
	v_mfma_f32_16x16x32_bf16 v[108:111], v[138:141], v[180:183], v[108:111]
	v_mfma_f32_16x16x32_bf16 v[104:107], v[152:155], v[180:183], v[104:107]
	v_mfma_f32_16x16x32_bf16 v[92:95], v[138:141], v[188:191], v[92:95]
	v_mfma_f32_16x16x32_bf16 v[88:91], v[152:155], v[188:191], v[88:91]
	v_mfma_f32_16x16x32_bf16 v[76:79], v[138:141], v[196:199], v[76:79]
	v_mfma_f32_16x16x32_bf16 v[72:75], v[152:155], v[196:199], v[72:75]
	v_mfma_f32_16x16x32_bf16 v[124:127], v[148:151], v[176:179], v[124:127]
	v_mfma_f32_16x16x32_bf16 v[120:123], v[156:159], v[176:179], v[120:123]
	v_mfma_f32_16x16x32_bf16 v[108:111], v[148:151], v[184:187], v[108:111]
	v_mfma_f32_16x16x32_bf16 v[104:107], v[156:159], v[184:187], v[104:107]
	v_mfma_f32_16x16x32_bf16 v[92:95], v[148:151], v[192:195], v[92:95]
	v_mfma_f32_16x16x32_bf16 v[88:91], v[156:159], v[192:195], v[88:91]
	v_mfma_f32_16x16x32_bf16 v[76:79], v[148:151], v[200:203], v[76:79]
	v_mfma_f32_16x16x32_bf16 v[72:75], v[156:159], v[200:203], v[72:75]
	s_setprio 0
	s_barrier
	s_add_i32 s7, 0, 0x14000
	v_add_u32_e32 v142, s7, v145
	s_add_i32 s8, s9, s1
	ds_read_b128 v[210:213], v142
	ds_read_b128 v[214:217], v142 offset:1024
	ds_read_b128 v[218:221], v142 offset:2048
	ds_read_b128 v[222:225], v142 offset:3072
	v_lshl_add_u64 v[142:143], s[64:65], 0, v[160:161]
	s_mov_b32 m0, s8
	v_lshl_add_u64 v[226:227], s[64:65], 0, v[128:129]
	global_load_lds_dwordx4 v[142:143], off
	s_add_i32 m0, s8, 0x2000
	s_nop 0
	global_load_lds_dwordx4 v[226:227], off
	s_barrier
	s_waitcnt lgkmcnt(0)
	s_setprio 1
	s_waitcnt lgkmcnt(0)
	v_mfma_f32_16x16x32_bf16 v[116:119], v[210:213], v[172:175], v[116:119]
	v_mfma_f32_16x16x32_bf16 v[112:115], v[218:221], v[172:175], v[112:115]
	v_mfma_f32_16x16x32_bf16 v[100:103], v[210:213], v[180:183], v[100:103]
	v_mfma_f32_16x16x32_bf16 v[96:99], v[218:221], v[180:183], v[96:99]
	v_mfma_f32_16x16x32_bf16 v[84:87], v[210:213], v[188:191], v[84:87]
	v_mfma_f32_16x16x32_bf16 v[80:83], v[218:221], v[188:191], v[80:83]
	v_mfma_f32_16x16x32_bf16 v[68:71], v[210:213], v[196:199], v[68:71]
	v_mfma_f32_16x16x32_bf16 v[64:67], v[218:221], v[196:199], v[64:67]
	v_mfma_f32_16x16x32_bf16 v[116:119], v[214:217], v[176:179], v[116:119]
	v_mfma_f32_16x16x32_bf16 v[112:115], v[222:225], v[176:179], v[112:115]
	v_mfma_f32_16x16x32_bf16 v[100:103], v[214:217], v[184:187], v[100:103]
	v_mfma_f32_16x16x32_bf16 v[96:99], v[222:225], v[184:187], v[96:99]
	v_mfma_f32_16x16x32_bf16 v[84:87], v[214:217], v[192:195], v[84:87]
	v_mfma_f32_16x16x32_bf16 v[80:83], v[222:225], v[192:195], v[80:83]
	v_mfma_f32_16x16x32_bf16 v[68:71], v[214:217], v[200:203], v[68:71]
	v_mfma_f32_16x16x32_bf16 v[64:67], v[222:225], v[200:203], v[64:67]
	s_setprio 0
	s_mov_b32 m0, s14
	v_lshl_add_u64 v[228:229], s[84:85], 0, v[132:133]
	s_barrier
	ds_read_b128 v[172:175], v147 offset:16384
	ds_read_b128 v[176:179], v147 offset:17408
	ds_read_b128 v[180:183], v147 offset:18432
	ds_read_b128 v[184:187], v147 offset:19456
	ds_read_b128 v[188:191], v147 offset:20480
	ds_read_b128 v[192:195], v147 offset:21504
	ds_read_b128 v[196:199], v147 offset:22528
	ds_read_b128 v[200:203], v147 offset:23552
	global_load_lds_dwordx4 v[228:229], off
	v_lshl_add_u64 v[230:231], s[84:85], 0, v[130:131]
	s_mov_b32 m0, s62
	s_nop 0
	global_load_lds_dwordx4 v[230:231], off
	s_barrier
	s_waitcnt lgkmcnt(0)
	s_setprio 1
	s_waitcnt lgkmcnt(0)
	v_mfma_f32_16x16x32_bf16 v[60:63], v[138:141], v[172:175], v[60:63]
	v_mfma_f32_16x16x32_bf16 v[56:59], v[152:155], v[172:175], v[56:59]
	v_mfma_f32_16x16x32_bf16 v[44:47], v[138:141], v[180:183], v[44:47]
	v_mfma_f32_16x16x32_bf16 v[40:43], v[152:155], v[180:183], v[40:43]
	v_mfma_f32_16x16x32_bf16 v[28:31], v[138:141], v[188:191], v[28:31]
	v_mfma_f32_16x16x32_bf16 v[24:27], v[152:155], v[188:191], v[24:27]
	v_mfma_f32_16x16x32_bf16 v[12:15], v[138:141], v[196:199], v[12:15]
	v_mfma_f32_16x16x32_bf16 v[8:11], v[152:155], v[196:199], v[8:11]
	v_mfma_f32_16x16x32_bf16 v[60:63], v[148:151], v[176:179], v[60:63]
	v_mfma_f32_16x16x32_bf16 v[56:59], v[156:159], v[176:179], v[56:59]
	v_mfma_f32_16x16x32_bf16 v[44:47], v[148:151], v[184:187], v[44:47]
	v_mfma_f32_16x16x32_bf16 v[40:43], v[156:159], v[184:187], v[40:43]
	v_mfma_f32_16x16x32_bf16 v[28:31], v[148:151], v[192:195], v[28:31]
	v_mfma_f32_16x16x32_bf16 v[24:27], v[156:159], v[192:195], v[24:27]
	v_mfma_f32_16x16x32_bf16 v[12:15], v[148:151], v[200:203], v[12:15]
	v_mfma_f32_16x16x32_bf16 v[8:11], v[156:159], v[200:203], v[8:11]
	s_setprio 0
	s_barrier
	s_add_u32 s8, s64, 0xc0000
	s_addc_u32 s9, s65, 0
	s_add_i32 s7, s7, s1
	v_lshl_add_u64 v[138:139], s[8:9], 0, v[160:161]
	s_mov_b32 m0, s7
	s_nop 0
	global_load_lds_dwordx4 v[138:139], off
	v_lshl_add_u64 v[138:139], s[8:9], 0, v[128:129]
	s_add_i32 m0, s7, 0x2000
	s_nop 0
	global_load_lds_dwordx4 v[138:139], off
	s_waitcnt vmcnt(6)
	s_barrier
	s_setprio 1
	v_mfma_f32_16x16x32_bf16 v[52:55], v[210:213], v[172:175], v[52:55]
	v_mfma_f32_16x16x32_bf16 v[48:51], v[218:221], v[172:175], v[48:51]
	v_mfma_f32_16x16x32_bf16 v[36:39], v[210:213], v[180:183], v[36:39]
	v_mfma_f32_16x16x32_bf16 v[32:35], v[218:221], v[180:183], v[32:35]
	v_mfma_f32_16x16x32_bf16 v[20:23], v[210:213], v[188:191], v[20:23]
	v_mfma_f32_16x16x32_bf16 v[16:19], v[218:221], v[188:191], v[16:19]
	v_mfma_f32_16x16x32_bf16 v[4:7], v[210:213], v[196:199], v[4:7]
	v_mfma_f32_16x16x32_bf16 v[0:3], v[218:221], v[196:199], v[0:3]
	v_mfma_f32_16x16x32_bf16 v[52:55], v[214:217], v[176:179], v[52:55]
	v_mfma_f32_16x16x32_bf16 v[48:51], v[222:225], v[176:179], v[48:51]
	v_mfma_f32_16x16x32_bf16 v[36:39], v[214:217], v[184:187], v[36:39]
	v_mfma_f32_16x16x32_bf16 v[32:35], v[222:225], v[184:187], v[32:35]
	v_mfma_f32_16x16x32_bf16 v[20:23], v[214:217], v[192:195], v[20:23]
	v_mfma_f32_16x16x32_bf16 v[16:19], v[222:225], v[192:195], v[16:19]
	v_mfma_f32_16x16x32_bf16 v[4:7], v[214:217], v[200:203], v[4:7]
	v_mfma_f32_16x16x32_bf16 v[0:3], v[222:225], v[200:203], v[0:3]
	s_setprio 0
	s_add_i32 s7, 0, 0x18000
	v_add_u32_e32 v156, s7, v145
	s_barrier
	ds_read_b128 v[138:141], v156
	ds_read_b128 v[148:151], v156 offset:1024
	ds_read_b128 v[152:155], v156 offset:2048
	ds_read_b128 v[156:159], v156 offset:3072
	s_add_u32 s8, s84, 0x200000
	s_addc_u32 s9, s85, 0
	s_mov_b32 m0, s63
	v_lshl_add_u64 v[210:211], s[8:9], 0, v[132:133]
	ds_read_b128 v[172:175], v147 offset:32768
	ds_read_b128 v[176:179], v147 offset:33792
	ds_read_b128 v[180:183], v147 offset:34816
	ds_read_b128 v[184:187], v147 offset:35840
	ds_read_b128 v[188:191], v147 offset:36864
	ds_read_b128 v[192:195], v147 offset:37888
	ds_read_b128 v[196:199], v147 offset:38912
	ds_read_b128 v[200:203], v147 offset:39936
	global_load_lds_dwordx4 v[210:211], off
	v_lshl_add_u64 v[210:211], s[8:9], 0, v[130:131]
	s_mov_b32 m0, s93
	s_nop 0
	global_load_lds_dwordx4 v[210:211], off
	s_waitcnt lgkmcnt(8)
	s_barrier
	s_waitcnt lgkmcnt(0)
	s_setprio 1
	s_waitcnt lgkmcnt(0)
	v_mfma_f32_16x16x32_bf16 v[124:127], v[138:141], v[172:175], v[124:127]
	v_mfma_f32_16x16x32_bf16 v[120:123], v[152:155], v[172:175], v[120:123]
	v_mfma_f32_16x16x32_bf16 v[108:111], v[138:141], v[180:183], v[108:111]
	v_mfma_f32_16x16x32_bf16 v[104:107], v[152:155], v[180:183], v[104:107]
	v_mfma_f32_16x16x32_bf16 v[92:95], v[138:141], v[188:191], v[92:95]
	v_mfma_f32_16x16x32_bf16 v[88:91], v[152:155], v[188:191], v[88:91]
	v_mfma_f32_16x16x32_bf16 v[76:79], v[138:141], v[196:199], v[76:79]
	v_mfma_f32_16x16x32_bf16 v[72:75], v[152:155], v[196:199], v[72:75]
	v_mfma_f32_16x16x32_bf16 v[124:127], v[148:151], v[176:179], v[124:127]
	v_mfma_f32_16x16x32_bf16 v[120:123], v[156:159], v[176:179], v[120:123]
	v_mfma_f32_16x16x32_bf16 v[108:111], v[148:151], v[184:187], v[108:111]
	v_mfma_f32_16x16x32_bf16 v[104:107], v[156:159], v[184:187], v[104:107]
	v_mfma_f32_16x16x32_bf16 v[92:95], v[148:151], v[192:195], v[92:95]
	v_mfma_f32_16x16x32_bf16 v[88:91], v[156:159], v[192:195], v[88:91]
	v_mfma_f32_16x16x32_bf16 v[76:79], v[148:151], v[200:203], v[76:79]
	v_mfma_f32_16x16x32_bf16 v[72:75], v[156:159], v[200:203], v[72:75]
	s_setprio 0
	s_barrier
	s_add_i32 s84, 0, 0x1c000
	s_add_i32 s7, s7, s1
	v_add_u32_e32 v209, s84, v145
	v_lshl_add_u64 v[142:143], v[142:143], 0, s[10:11]
	s_mov_b32 m0, s7
	ds_read_b128 v[210:213], v209
	ds_read_b128 v[214:217], v209 offset:1024
	ds_read_b128 v[218:221], v209 offset:2048
	ds_read_b128 v[222:225], v209 offset:3072
	global_load_lds_dwordx4 v[142:143], off
	v_lshl_add_u64 v[142:143], v[226:227], 0, s[10:11]
	s_add_i32 m0, s7, 0x2000
	s_nop 0
	global_load_lds_dwordx4 v[142:143], off
	s_barrier
	s_waitcnt lgkmcnt(0)
	s_setprio 1
	s_waitcnt lgkmcnt(0)
	v_mfma_f32_16x16x32_bf16 v[116:119], v[210:213], v[172:175], v[116:119]
	v_mfma_f32_16x16x32_bf16 v[112:115], v[218:221], v[172:175], v[112:115]
	v_mfma_f32_16x16x32_bf16 v[100:103], v[210:213], v[180:183], v[100:103]
	v_mfma_f32_16x16x32_bf16 v[96:99], v[218:221], v[180:183], v[96:99]
	v_mfma_f32_16x16x32_bf16 v[84:87], v[210:213], v[188:191], v[84:87]
	v_mfma_f32_16x16x32_bf16 v[80:83], v[218:221], v[188:191], v[80:83]
	v_mfma_f32_16x16x32_bf16 v[68:71], v[210:213], v[196:199], v[68:71]
	v_mfma_f32_16x16x32_bf16 v[64:67], v[218:221], v[196:199], v[64:67]
	v_mfma_f32_16x16x32_bf16 v[116:119], v[214:217], v[176:179], v[116:119]
	v_mfma_f32_16x16x32_bf16 v[112:115], v[222:225], v[176:179], v[112:115]
	v_mfma_f32_16x16x32_bf16 v[100:103], v[214:217], v[184:187], v[100:103]
	v_mfma_f32_16x16x32_bf16 v[96:99], v[222:225], v[184:187], v[96:99]
	v_mfma_f32_16x16x32_bf16 v[84:87], v[214:217], v[192:195], v[84:87]
	v_mfma_f32_16x16x32_bf16 v[80:83], v[222:225], v[192:195], v[80:83]
	v_mfma_f32_16x16x32_bf16 v[68:71], v[214:217], v[200:203], v[68:71]
	v_mfma_f32_16x16x32_bf16 v[64:67], v[222:225], v[200:203], v[64:67]
	s_setprio 0
	s_mov_b32 m0, s94
	v_lshl_add_u64 v[142:143], v[228:229], 0, s[10:11]
	s_barrier
	ds_read_b128 v[172:175], v147 offset:49152
	ds_read_b128 v[176:179], v147 offset:50176
	ds_read_b128 v[180:183], v147 offset:51200
	ds_read_b128 v[184:187], v147 offset:52224
	ds_read_b128 v[188:191], v147 offset:53248
	ds_read_b128 v[192:195], v147 offset:54272
	ds_read_b128 v[196:199], v147 offset:55296
	ds_read_b128 v[200:203], v147 offset:56320
	global_load_lds_dwordx4 v[142:143], off
	v_lshl_add_u64 v[142:143], v[230:231], 0, s[10:11]
	s_mov_b32 m0, s95
	s_nop 0
	global_load_lds_dwordx4 v[142:143], off
	s_barrier
	s_waitcnt lgkmcnt(0)
	s_setprio 1
	s_waitcnt lgkmcnt(0)
	v_mfma_f32_16x16x32_bf16 v[60:63], v[138:141], v[172:175], v[60:63]
	v_mfma_f32_16x16x32_bf16 v[56:59], v[152:155], v[172:175], v[56:59]
	v_mfma_f32_16x16x32_bf16 v[44:47], v[138:141], v[180:183], v[44:47]
	v_mfma_f32_16x16x32_bf16 v[40:43], v[152:155], v[180:183], v[40:43]
	v_mfma_f32_16x16x32_bf16 v[28:31], v[138:141], v[188:191], v[28:31]
	v_mfma_f32_16x16x32_bf16 v[24:27], v[152:155], v[188:191], v[24:27]
	v_mfma_f32_16x16x32_bf16 v[12:15], v[138:141], v[196:199], v[12:15]
	v_mfma_f32_16x16x32_bf16 v[8:11], v[152:155], v[196:199], v[8:11]
	v_mfma_f32_16x16x32_bf16 v[60:63], v[148:151], v[176:179], v[60:63]
	v_mfma_f32_16x16x32_bf16 v[56:59], v[156:159], v[176:179], v[56:59]
	v_mfma_f32_16x16x32_bf16 v[44:47], v[148:151], v[184:187], v[44:47]
	v_mfma_f32_16x16x32_bf16 v[40:43], v[156:159], v[184:187], v[40:43]
	v_mfma_f32_16x16x32_bf16 v[28:31], v[148:151], v[192:195], v[28:31]
	v_mfma_f32_16x16x32_bf16 v[24:27], v[156:159], v[192:195], v[24:27]
	v_mfma_f32_16x16x32_bf16 v[12:15], v[148:151], v[200:203], v[12:15]
	v_mfma_f32_16x16x32_bf16 v[8:11], v[156:159], v[200:203], v[8:11]
	s_setprio 0
	s_barrier
	s_add_u32 s8, s64, 0xc0080
	s_addc_u32 s9, s65, 0
	s_add_i32 s7, s84, s1
	v_lshl_add_u64 v[138:139], s[8:9], 0, v[160:161]
	s_mov_b32 m0, s7
	s_nop 0
	global_load_lds_dwordx4 v[138:139], off
	v_lshl_add_u64 v[138:139], s[8:9], 0, v[128:129]
	s_add_i32 m0, s7, 0x2000
	s_nop 0
	global_load_lds_dwordx4 v[138:139], off
	s_waitcnt vmcnt(6)
	s_barrier
	s_setprio 1
	v_mfma_f32_16x16x32_bf16 v[52:55], v[210:213], v[172:175], v[52:55]
	v_mfma_f32_16x16x32_bf16 v[48:51], v[218:221], v[172:175], v[48:51]
	v_mfma_f32_16x16x32_bf16 v[36:39], v[210:213], v[180:183], v[36:39]
	v_mfma_f32_16x16x32_bf16 v[32:35], v[218:221], v[180:183], v[32:35]
	v_mfma_f32_16x16x32_bf16 v[20:23], v[210:213], v[188:191], v[20:23]
	v_mfma_f32_16x16x32_bf16 v[16:19], v[218:221], v[188:191], v[16:19]
	v_mfma_f32_16x16x32_bf16 v[4:7], v[210:213], v[196:199], v[4:7]
	v_mfma_f32_16x16x32_bf16 v[0:3], v[218:221], v[196:199], v[0:3]
	v_mfma_f32_16x16x32_bf16 v[52:55], v[214:217], v[176:179], v[52:55]
	v_mfma_f32_16x16x32_bf16 v[48:51], v[222:225], v[176:179], v[48:51]
	v_mfma_f32_16x16x32_bf16 v[36:39], v[214:217], v[184:187], v[36:39]
	v_mfma_f32_16x16x32_bf16 v[32:35], v[222:225], v[184:187], v[32:35]
	v_mfma_f32_16x16x32_bf16 v[20:23], v[214:217], v[192:195], v[20:23]
	v_mfma_f32_16x16x32_bf16 v[16:19], v[222:225], v[192:195], v[16:19]
	v_mfma_f32_16x16x32_bf16 v[4:7], v[214:217], v[200:203], v[4:7]
	v_mfma_f32_16x16x32_bf16 v[0:3], v[222:225], v[200:203], v[0:3]
	s_setprio 0
	s_add_i32 s6, s6, 2
	s_add_u32 s40, s40, 0x100
	s_addc_u32 s41, s41, 0
	s_add_u32 s4, s4, 0x100
	s_addc_u32 s5, s5, 0
	s_cmp_gt_u32 s6, 45
	s_barrier
	s_cbranch_scc0 .LBB0_448
	v_lshl_add_u32 v142, s43, 8, v144
	v_lshl_or_b32 v140, s97, 8, v146
	v_ashrrev_i32_e32 v143, 31, v142
	v_ashrrev_i32_e32 v141, 31, v140
	v_lshlrev_b64 v[138:139], 10, v[142:143]
	v_lshl_add_u64 v[138:139], v[138:139], 0, v[140:141]
	v_lshlrev_b64 v[138:139], 2, v[138:139]
	v_lshl_add_u64 v[152:153], s[18:19], 0, v[138:139]
	global_load_dwordx4 v[148:151], v[152:153], off
	global_load_dwordx4 v[156:159], v[152:153], off offset:16
	global_load_dwordx4 v[172:175], v[152:153], off offset:512
	global_load_dwordx4 v[176:179], v[152:153], off offset:528
	s_mov_b64 s[4:5], 0x80000
	s_and_b64 vcc, exec, s[38:39]
	s_mov_b32 s97, s42
	s_mov_b32 s43, s24
	s_mov_b64 s[64:65], s[34:35]
	s_mov_b64 s[84:85], s[36:37]
	s_waitcnt vmcnt(0)
	v_pk_add_f32 v[126:127], v[126:127], v[150:151]
	v_pk_add_f32 v[124:125], v[124:125], v[148:149]
	v_lshl_add_u64 v[148:149], s[12:13], 0, v[138:139]
	global_store_dwordx4 v[148:149], v[124:127], off
	v_pk_add_f32 v[122:123], v[122:123], v[158:159]
	v_pk_add_f32 v[120:121], v[120:121], v[156:157]
	global_store_dwordx4 v[148:149], v[120:123], off offset:16
	v_pk_add_f32 v[118:119], v[118:119], v[174:175]
	v_pk_add_f32 v[116:117], v[116:117], v[172:173]
	global_store_dwordx4 v[148:149], v[116:119], off offset:512
	v_pk_add_f32 v[114:115], v[114:115], v[178:179]
	v_pk_add_f32 v[112:113], v[112:113], v[176:177]
	global_store_dwordx4 v[148:149], v[112:115], off offset:528
	s_nop 1
	v_or_b32_e32 v112, 16, v142
	v_ashrrev_i32_e32 v113, 31, v112
	v_lshlrev_b64 v[112:113], 10, v[112:113]
	v_lshl_add_u64 v[112:113], v[112:113], 0, v[140:141]
	v_lshlrev_b64 v[116:117], 2, v[112:113]
	v_lshl_add_u64 v[118:119], s[18:19], 0, v[116:117]
	global_load_dwordx4 v[112:115], v[118:119], off
	global_load_dwordx4 v[156:159], v[118:119], off offset:16
	global_load_dwordx4 v[172:175], v[118:119], off offset:512
	global_load_dwordx4 v[176:179], v[118:119], off offset:528
	s_waitcnt vmcnt(0)
	v_pk_add_f32 v[110:111], v[110:111], v[114:115]
	v_pk_add_f32 v[108:109], v[108:109], v[112:113]
	v_lshl_add_u64 v[112:113], s[12:13], 0, v[116:117]
	global_store_dwordx4 v[112:113], v[108:111], off
	v_pk_add_f32 v[106:107], v[106:107], v[158:159]
	v_pk_add_f32 v[104:105], v[104:105], v[156:157]
	global_store_dwordx4 v[112:113], v[104:107], off offset:16
	v_pk_add_f32 v[102:103], v[102:103], v[174:175]
	v_pk_add_f32 v[100:101], v[100:101], v[172:173]
	global_store_dwordx4 v[112:113], v[100:103], off offset:512
	v_pk_add_f32 v[98:99], v[98:99], v[178:179]
	v_pk_add_f32 v[96:97], v[96:97], v[176:177]
	global_store_dwordx4 v[112:113], v[96:99], off offset:528
	s_nop 1
	v_or_b32_e32 v96, 32, v142
	v_ashrrev_i32_e32 v97, 31, v96
	v_lshlrev_b64 v[96:97], 10, v[96:97]
	v_lshl_add_u64 v[96:97], v[96:97], 0, v[140:141]
	v_lshlrev_b64 v[100:101], 2, v[96:97]
	v_lshl_add_u64 v[102:103], s[18:19], 0, v[100:101]
	global_load_dwordx4 v[96:99], v[102:103], off
	global_load_dwordx4 v[156:159], v[102:103], off offset:16
	global_load_dwordx4 v[172:175], v[102:103], off offset:512
	global_load_dwordx4 v[176:179], v[102:103], off offset:528
	s_waitcnt vmcnt(0)
	v_pk_add_f32 v[94:95], v[94:95], v[98:99]
	v_pk_add_f32 v[92:93], v[92:93], v[96:97]
	v_lshl_add_u64 v[96:97], s[12:13], 0, v[100:101]
	global_store_dwordx4 v[96:97], v[92:95], off
	v_pk_add_f32 v[90:91], v[90:91], v[158:159]
	v_pk_add_f32 v[88:89], v[88:89], v[156:157]
	global_store_dwordx4 v[96:97], v[88:91], off offset:16
	v_pk_add_f32 v[86:87], v[86:87], v[174:175]
	v_pk_add_f32 v[84:85], v[84:85], v[172:173]
	global_store_dwordx4 v[96:97], v[84:87], off offset:512
	v_pk_add_f32 v[82:83], v[82:83], v[178:179]
	v_pk_add_f32 v[80:81], v[80:81], v[176:177]
	global_store_dwordx4 v[96:97], v[80:83], off offset:528
	s_nop 1
	v_or_b32_e32 v80, 48, v142
	v_ashrrev_i32_e32 v81, 31, v80
	v_lshlrev_b64 v[80:81], 10, v[80:81]
	v_lshl_add_u64 v[80:81], v[80:81], 0, v[140:141]
	v_lshlrev_b64 v[84:85], 2, v[80:81]
	v_lshl_add_u64 v[86:87], s[18:19], 0, v[84:85]
	global_load_dwordx4 v[80:83], v[86:87], off
	global_load_dwordx4 v[156:159], v[86:87], off offset:16
	global_load_dwordx4 v[172:175], v[86:87], off offset:512
	global_load_dwordx4 v[176:179], v[86:87], off offset:528
	s_waitcnt vmcnt(0)
	v_pk_add_f32 v[78:79], v[78:79], v[82:83]
	v_pk_add_f32 v[76:77], v[76:77], v[80:81]
	v_lshl_add_u64 v[80:81], s[12:13], 0, v[84:85]
	global_store_dwordx4 v[80:81], v[76:79], off
	v_pk_add_f32 v[74:75], v[74:75], v[158:159]
	v_pk_add_f32 v[72:73], v[72:73], v[156:157]
	global_store_dwordx4 v[80:81], v[72:75], off offset:16
	v_pk_add_f32 v[70:71], v[70:71], v[174:175]
	v_pk_add_f32 v[68:69], v[68:69], v[172:173]
	global_store_dwordx4 v[80:81], v[68:71], off offset:512
	v_pk_add_f32 v[66:67], v[66:67], v[178:179]
	v_pk_add_f32 v[64:65], v[64:65], v[176:177]
	v_lshl_add_u64 v[68:69], v[138:139], 0, s[4:5]
	global_store_dwordx4 v[80:81], v[64:67], off offset:528
	v_lshl_add_u64 v[70:71], s[18:19], 0, v[68:69]
	global_load_dwordx4 v[64:67], v[70:71], off
	global_load_dwordx4 v[156:159], v[70:71], off offset:16
	global_load_dwordx4 v[172:175], v[70:71], off offset:512
	global_load_dwordx4 v[176:179], v[70:71], off offset:528
	s_mov_b64 s[4:5], 0x90000
	s_waitcnt vmcnt(0)
	v_pk_add_f32 v[62:63], v[62:63], v[66:67]
	v_pk_add_f32 v[60:61], v[60:61], v[64:65]
	v_lshl_add_u64 v[64:65], s[12:13], 0, v[68:69]
	global_store_dwordx4 v[64:65], v[60:63], off
	v_pk_add_f32 v[58:59], v[58:59], v[158:159]
	v_pk_add_f32 v[56:57], v[56:57], v[156:157]
	global_store_dwordx4 v[64:65], v[56:59], off offset:16
	v_pk_add_f32 v[54:55], v[54:55], v[174:175]
	v_pk_add_f32 v[52:53], v[52:53], v[172:173]
	global_store_dwordx4 v[64:65], v[52:55], off offset:512
	v_pk_add_f32 v[50:51], v[50:51], v[178:179]
	v_pk_add_f32 v[48:49], v[48:49], v[176:177]
	v_lshl_add_u64 v[52:53], v[138:139], 0, s[4:5]
	global_store_dwordx4 v[64:65], v[48:51], off offset:528
	v_lshl_add_u64 v[54:55], s[18:19], 0, v[52:53]
	global_load_dwordx4 v[48:51], v[54:55], off
	global_load_dwordx4 v[156:159], v[54:55], off offset:16
	global_load_dwordx4 v[172:175], v[54:55], off offset:512
	global_load_dwordx4 v[176:179], v[54:55], off offset:528
	s_mov_b64 s[4:5], 0xa0000
	s_waitcnt vmcnt(0)
	v_pk_add_f32 v[46:47], v[46:47], v[50:51]
	v_pk_add_f32 v[44:45], v[44:45], v[48:49]
	v_lshl_add_u64 v[48:49], s[12:13], 0, v[52:53]
	global_store_dwordx4 v[48:49], v[44:47], off
	v_pk_add_f32 v[42:43], v[42:43], v[158:159]
	v_pk_add_f32 v[40:41], v[40:41], v[156:157]
	global_store_dwordx4 v[48:49], v[40:43], off offset:16
	v_pk_add_f32 v[38:39], v[38:39], v[174:175]
	v_pk_add_f32 v[36:37], v[36:37], v[172:173]
	global_store_dwordx4 v[48:49], v[36:39], off offset:512
	v_pk_add_f32 v[34:35], v[34:35], v[178:179]
	v_pk_add_f32 v[32:33], v[32:33], v[176:177]
	v_lshl_add_u64 v[36:37], v[138:139], 0, s[4:5]
	global_store_dwordx4 v[48:49], v[32:35], off offset:528
	v_lshl_add_u64 v[38:39], s[18:19], 0, v[36:37]
	global_load_dwordx4 v[32:35], v[38:39], off
	global_load_dwordx4 v[156:159], v[38:39], off offset:16
	global_load_dwordx4 v[172:175], v[38:39], off offset:512
	global_load_dwordx4 v[176:179], v[38:39], off offset:528
	s_mov_b64 s[4:5], 0xb0000
	s_waitcnt vmcnt(0)
	v_pk_add_f32 v[30:31], v[30:31], v[34:35]
	v_pk_add_f32 v[28:29], v[28:29], v[32:33]
	v_lshl_add_u64 v[32:33], s[12:13], 0, v[36:37]
	global_store_dwordx4 v[32:33], v[28:31], off
	v_pk_add_f32 v[26:27], v[26:27], v[158:159]
	v_pk_add_f32 v[24:25], v[24:25], v[156:157]
	global_store_dwordx4 v[32:33], v[24:27], off offset:16
	v_pk_add_f32 v[22:23], v[22:23], v[174:175]
	v_pk_add_f32 v[20:21], v[20:21], v[172:173]
	global_store_dwordx4 v[32:33], v[20:23], off offset:512
	v_pk_add_f32 v[18:19], v[18:19], v[178:179]
	v_pk_add_f32 v[16:17], v[16:17], v[176:177]
	v_lshl_add_u64 v[20:21], v[138:139], 0, s[4:5]
	global_store_dwordx4 v[32:33], v[16:19], off offset:528
	v_lshl_add_u64 v[22:23], s[18:19], 0, v[20:21]
	global_load_dwordx4 v[16:19], v[22:23], off
	global_load_dwordx4 v[156:159], v[22:23], off offset:16
	global_load_dwordx4 v[172:175], v[22:23], off offset:512
	global_load_dwordx4 v[176:179], v[22:23], off offset:528
	s_waitcnt vmcnt(0)
	v_pk_add_f32 v[14:15], v[14:15], v[18:19]
	v_pk_add_f32 v[12:13], v[12:13], v[16:17]
	v_lshl_add_u64 v[16:17], s[12:13], 0, v[20:21]
	global_store_dwordx4 v[16:17], v[12:15], off
	v_pk_add_f32 v[10:11], v[10:11], v[158:159]
	v_pk_add_f32 v[8:9], v[8:9], v[156:157]
	global_store_dwordx4 v[16:17], v[8:11], off offset:16
	v_pk_add_f32 v[6:7], v[6:7], v[174:175]
	v_pk_add_f32 v[4:5], v[4:5], v[172:173]
	global_store_dwordx4 v[16:17], v[4:7], off offset:512
	v_pk_add_f32 v[2:3], v[2:3], v[178:179]
	v_pk_add_f32 v[0:1], v[0:1], v[176:177]
	global_store_dwordx4 v[16:17], v[0:3], off offset:528
	s_cbranch_vccz .LBB0_439
	s_waitcnt vmcnt(0)
	v_readlane_b32 s96, v255, 16
	s_cmpk_gt_u32 s0, 0xff
	v_readlane_b32 s94, v255, 14
	v_readlane_b32 s97, v255, 17
	v_readlane_b32 s95, v255, 15
	s_cbranch_scc1 .LBB0_452
	s_barrier
